# code placement: every 32-MFMA run of both GEMM K-loops starts on an 8-byte boundary (s_nop 0 pads at the head of the preceding load segments), on top of v11
# baseline (speedup 1.0000x reference)
.Lpeel_join375_1:
	s_waitcnt lgkmcnt(0)
	s_barrier
	s_setprio 1
	s_waitcnt lgkmcnt(0)
	v_mfma_f32_16x16x32_bf16 v[120:123], v[128:131], v[178:181], 0
	v_mfma_f32_16x16x32_bf16 v[124:127], v[136:139], v[178:181], 0
	v_mfma_f32_16x16x32_bf16 v[100:103], v[128:131], v[206:209], 0
	v_mfma_f32_16x16x32_bf16 v[96:99], v[136:139], v[206:209], 0
	v_mfma_f32_16x16x32_bf16 v[84:87], v[128:131], v[214:217], 0
	v_mfma_f32_16x16x32_bf16 v[80:83], v[136:139], v[214:217], 0
	v_mfma_f32_16x16x32_bf16 v[68:71], v[128:131], v[222:225], 0
	v_mfma_f32_16x16x32_bf16 v[64:67], v[136:139], v[222:225], 0
	v_mfma_f32_16x16x32_bf16 v[120:123], v[132:135], v[202:205], v[120:123]
	v_mfma_f32_16x16x32_bf16 v[124:127], v[140:143], v[202:205], v[124:127]
	v_mfma_f32_16x16x32_bf16 v[100:103], v[132:135], v[210:213], v[100:103]
	v_mfma_f32_16x16x32_bf16 v[96:99], v[140:143], v[210:213], v[96:99]
	v_mfma_f32_16x16x32_bf16 v[84:87], v[132:135], v[218:221], v[84:87]
	v_mfma_f32_16x16x32_bf16 v[80:83], v[140:143], v[218:221], v[80:83]
	v_mfma_f32_16x16x32_bf16 v[68:71], v[132:135], v[226:229], v[68:71]
	v_mfma_f32_16x16x32_bf16 v[64:67], v[140:143], v[226:229], v[64:67]
	v_mfma_f32_16x16x32_bf16 v[116:119], v[144:147], v[178:181], 0
	v_mfma_f32_16x16x32_bf16 v[112:115], v[170:173], v[178:181], 0
	v_mfma_f32_16x16x32_bf16 v[108:111], v[144:147], v[206:209], 0
	v_mfma_f32_16x16x32_bf16 v[104:107], v[170:173], v[206:209], 0
	v_mfma_f32_16x16x32_bf16 v[92:95], v[144:147], v[214:217], 0
	v_mfma_f32_16x16x32_bf16 v[88:91], v[170:173], v[214:217], 0
	v_mfma_f32_16x16x32_bf16 v[76:79], v[144:147], v[222:225], 0
	v_mfma_f32_16x16x32_bf16 v[72:75], v[170:173], v[222:225], 0
	v_mfma_f32_16x16x32_bf16 v[116:119], v[148:151], v[202:205], v[116:119]
	v_mfma_f32_16x16x32_bf16 v[112:115], v[174:177], v[202:205], v[112:115]
	v_mfma_f32_16x16x32_bf16 v[108:111], v[148:151], v[210:213], v[108:111]
	v_mfma_f32_16x16x32_bf16 v[104:107], v[174:177], v[210:213], v[104:107]
	v_mfma_f32_16x16x32_bf16 v[92:95], v[148:151], v[218:221], v[92:95]
	v_mfma_f32_16x16x32_bf16 v[88:91], v[174:177], v[218:221], v[88:91]
	v_mfma_f32_16x16x32_bf16 v[76:79], v[148:151], v[226:229], v[76:79]
	v_mfma_f32_16x16x32_bf16 v[72:75], v[174:177], v[226:229], v[72:75]
	s_setprio 0
	s_barrier
	s_nop 0
	s_add_i32 s12, s12, s17
	v_lshl_add_u64 v[230:231], s[14:15], 0, v[154:155]
	s_mov_b32 m0, s12
	ds_read_b128 v[178:181], v157 offset:16384
	ds_read_b128 v[202:205], v157 offset:17408
	ds_read_b128 v[206:209], v157 offset:18432
	ds_read_b128 v[210:213], v157 offset:19456
	ds_read_b128 v[214:217], v157 offset:20480
	ds_read_b128 v[218:221], v157 offset:21504
	ds_read_b128 v[222:225], v157 offset:22528
	ds_read_b128 v[226:229], v157 offset:23552
	global_load_lds_dwordx4 v[230:231], off
	s_add_i32 m0, s12, 0x2000
	v_lshl_add_u64 v[232:233], s[14:15], 0, v[162:163]
	s_add_u32 s14, s14, s24
	s_addc_u32 s15, s15, s25
	s_add_i32 s2, s2, s17
	global_load_lds_dwordx4 v[232:233], off
	v_lshl_add_u64 v[234:235], s[14:15], 0, v[154:155]
	s_mov_b32 m0, s2
	v_lshl_add_u64 v[236:237], s[14:15], 0, v[162:163]
	global_load_lds_dwordx4 v[234:235], off
	s_add_i32 m0, s2, 0x2000
	v_lshl_add_u64 v[238:239], s[0:1], 0, v[158:159]
	global_load_lds_dwordx4 v[236:237], off
	s_mov_b32 m0, s45
	v_lshl_add_u64 v[240:241], s[0:1], 0, v[160:161]
	global_load_lds_dwordx4 v[238:239], off
	s_mov_b32 m0, s83
	s_nop 0
	global_load_lds_dwordx4 v[240:241], off
	s_lshl_b32 s99, s17, 1
	s_add_i32 m0, s99, 0x20000
	s_lshl_b32 s98, s65, 14
	s_add_i32 s98, s98, s99
	s_add_u32 s98, s100, s98
	s_addc_u32 s99, s101, 0
	global_load_lds_dwordx4 v248, s[98:99]
	global_load_lds_dwordx4 v248, s[98:99] offset:1024
	s_cmp_eq_u32 s18, 1
	s_cbranch_scc1 .Lpeel_strict375_2
	s_waitcnt vmcnt(18)
	s_branch .Lpeel_join375_2

.Lpeel_join375_2:
	s_waitcnt lgkmcnt(0)
	s_barrier
	s_setprio 1
	s_waitcnt lgkmcnt(0)
	v_mfma_f32_16x16x32_bf16 v[52:55], v[128:131], v[178:181], 0
	v_mfma_f32_16x16x32_bf16 v[48:51], v[136:139], v[178:181], 0
	v_mfma_f32_16x16x32_bf16 v[36:39], v[128:131], v[206:209], 0
	v_mfma_f32_16x16x32_bf16 v[32:35], v[136:139], v[206:209], 0
	v_mfma_f32_16x16x32_bf16 v[20:23], v[128:131], v[214:217], 0
	v_mfma_f32_16x16x32_bf16 v[16:19], v[136:139], v[214:217], 0
	v_mfma_f32_16x16x32_bf16 v[4:7], v[128:131], v[222:225], 0
	v_mfma_f32_16x16x32_bf16 v[0:3], v[136:139], v[222:225], 0
	v_mfma_f32_16x16x32_bf16 v[52:55], v[132:135], v[202:205], v[52:55]
	v_mfma_f32_16x16x32_bf16 v[48:51], v[140:143], v[202:205], v[48:51]
	v_mfma_f32_16x16x32_bf16 v[36:39], v[132:135], v[210:213], v[36:39]
	v_mfma_f32_16x16x32_bf16 v[32:35], v[140:143], v[210:213], v[32:35]
	v_mfma_f32_16x16x32_bf16 v[20:23], v[132:135], v[218:221], v[20:23]
	v_mfma_f32_16x16x32_bf16 v[16:19], v[140:143], v[218:221], v[16:19]
	v_mfma_f32_16x16x32_bf16 v[4:7], v[132:135], v[226:229], v[4:7]
	v_mfma_f32_16x16x32_bf16 v[0:3], v[140:143], v[226:229], v[0:3]
	v_mfma_f32_16x16x32_bf16 v[60:63], v[144:147], v[178:181], 0
	v_mfma_f32_16x16x32_bf16 v[56:59], v[170:173], v[178:181], 0
	v_mfma_f32_16x16x32_bf16 v[44:47], v[144:147], v[206:209], 0
	v_mfma_f32_16x16x32_bf16 v[40:43], v[170:173], v[206:209], 0
	v_mfma_f32_16x16x32_bf16 v[28:31], v[144:147], v[214:217], 0
	v_mfma_f32_16x16x32_bf16 v[24:27], v[170:173], v[214:217], 0
	v_mfma_f32_16x16x32_bf16 v[12:15], v[144:147], v[222:225], 0
	v_mfma_f32_16x16x32_bf16 v[8:11], v[170:173], v[222:225], 0
	v_mfma_f32_16x16x32_bf16 v[60:63], v[148:151], v[202:205], v[60:63]
	v_mfma_f32_16x16x32_bf16 v[56:59], v[174:177], v[202:205], v[56:59]
	v_mfma_f32_16x16x32_bf16 v[44:47], v[148:151], v[210:213], v[44:47]
	v_mfma_f32_16x16x32_bf16 v[40:43], v[174:177], v[210:213], v[40:43]
	v_mfma_f32_16x16x32_bf16 v[28:31], v[148:151], v[218:221], v[28:31]
	v_mfma_f32_16x16x32_bf16 v[24:27], v[174:177], v[218:221], v[24:27]
	v_mfma_f32_16x16x32_bf16 v[12:15], v[148:151], v[226:229], v[12:15]
	v_mfma_f32_16x16x32_bf16 v[8:11], v[174:177], v[226:229], v[8:11]
	s_setprio 0
	s_barrier
	s_add_i32 s2, 0, 0x18000
	s_add_i32 s12, 0, 0x1c000
	v_add_u32_e32 v140, s2, v195
	v_add_u32_e32 v174, s12, v195
	ds_read_b128 v[128:131], v140
	ds_read_b128 v[132:135], v140 offset:1024
	ds_read_b128 v[136:139], v140 offset:2048
	ds_read_b128 v[140:143], v140 offset:3072
	ds_read_b128 v[144:147], v174
	ds_read_b128 v[148:151], v174 offset:1024
	ds_read_b128 v[170:173], v174 offset:2048
	ds_read_b128 v[174:177], v174 offset:3072
	s_add_u32 s0, s0, s8
	s_addc_u32 s1, s1, s9
	s_mov_b32 m0, s28
	v_lshl_add_u64 v[242:243], s[0:1], 0, v[158:159]
	ds_read_b128 v[178:181], v157 offset:32768
	ds_read_b128 v[202:205], v157 offset:33792
	ds_read_b128 v[206:209], v157 offset:34816
	ds_read_b128 v[210:213], v157 offset:35840
	ds_read_b128 v[214:217], v157 offset:36864
	ds_read_b128 v[218:221], v157 offset:37888
	ds_read_b128 v[222:225], v157 offset:38912
	ds_read_b128 v[226:229], v157 offset:39936
	global_load_lds_dwordx4 v[242:243], off
	v_lshl_add_u64 v[242:243], s[0:1], 0, v[160:161]
	s_mov_b32 m0, s29
	s_nop 0
	global_load_lds_dwordx4 v[242:243], off
	s_waitcnt vmcnt(10)
	s_waitcnt lgkmcnt(0)
	s_barrier
	s_setprio 1
	s_waitcnt lgkmcnt(0)
	v_mfma_f32_16x16x32_bf16 v[120:123], v[128:131], v[178:181], v[120:123]
	v_mfma_f32_16x16x32_bf16 v[124:127], v[136:139], v[178:181], v[124:127]
	v_mfma_f32_16x16x32_bf16 v[100:103], v[128:131], v[206:209], v[100:103]
	v_mfma_f32_16x16x32_bf16 v[96:99], v[136:139], v[206:209], v[96:99]
	v_mfma_f32_16x16x32_bf16 v[84:87], v[128:131], v[214:217], v[84:87]
	v_mfma_f32_16x16x32_bf16 v[80:83], v[136:139], v[214:217], v[80:83]
	v_mfma_f32_16x16x32_bf16 v[68:71], v[128:131], v[222:225], v[68:71]
	v_mfma_f32_16x16x32_bf16 v[64:67], v[136:139], v[222:225], v[64:67]
	v_mfma_f32_16x16x32_bf16 v[120:123], v[132:135], v[202:205], v[120:123]
	v_mfma_f32_16x16x32_bf16 v[124:127], v[140:143], v[202:205], v[124:127]
	v_mfma_f32_16x16x32_bf16 v[100:103], v[132:135], v[210:213], v[100:103]
	v_mfma_f32_16x16x32_bf16 v[96:99], v[140:143], v[210:213], v[96:99]
	v_mfma_f32_16x16x32_bf16 v[84:87], v[132:135], v[218:221], v[84:87]
	v_mfma_f32_16x16x32_bf16 v[80:83], v[140:143], v[218:221], v[80:83]
	v_mfma_f32_16x16x32_bf16 v[68:71], v[132:135], v[226:229], v[68:71]
	v_mfma_f32_16x16x32_bf16 v[64:67], v[140:143], v[226:229], v[64:67]
	v_mfma_f32_16x16x32_bf16 v[116:119], v[144:147], v[178:181], v[116:119]
	v_mfma_f32_16x16x32_bf16 v[112:115], v[170:173], v[178:181], v[112:115]
	v_mfma_f32_16x16x32_bf16 v[108:111], v[144:147], v[206:209], v[108:111]
	v_mfma_f32_16x16x32_bf16 v[104:107], v[170:173], v[206:209], v[104:107]
	v_mfma_f32_16x16x32_bf16 v[92:95], v[144:147], v[214:217], v[92:95]
	v_mfma_f32_16x16x32_bf16 v[88:91], v[170:173], v[214:217], v[88:91]
	v_mfma_f32_16x16x32_bf16 v[76:79], v[144:147], v[222:225], v[76:79]
	v_mfma_f32_16x16x32_bf16 v[72:75], v[170:173], v[222:225], v[72:75]
	v_mfma_f32_16x16x32_bf16 v[116:119], v[148:151], v[202:205], v[116:119]
	v_mfma_f32_16x16x32_bf16 v[112:115], v[174:177], v[202:205], v[112:115]
	v_mfma_f32_16x16x32_bf16 v[108:111], v[148:151], v[210:213], v[108:111]
	v_mfma_f32_16x16x32_bf16 v[104:107], v[174:177], v[210:213], v[104:107]
	v_mfma_f32_16x16x32_bf16 v[92:95], v[148:151], v[218:221], v[92:95]
	v_mfma_f32_16x16x32_bf16 v[88:91], v[174:177], v[218:221], v[88:91]
	v_mfma_f32_16x16x32_bf16 v[76:79], v[148:151], v[226:229], v[76:79]
	v_mfma_f32_16x16x32_bf16 v[72:75], v[174:177], v[226:229], v[72:75]
	s_setprio 0
	s_barrier
	s_nop 0
	s_add_i32 s0, s2, s17
	v_lshl_add_u64 v[230:231], v[230:231], 0, s[36:37]
	s_mov_b32 m0, s0
	ds_read_b128 v[178:181], v157 offset:49152
	ds_read_b128 v[202:205], v157 offset:50176
	ds_read_b128 v[206:209], v157 offset:51200
	ds_read_b128 v[210:213], v157 offset:52224
	ds_read_b128 v[214:217], v157 offset:53248
	ds_read_b128 v[218:221], v157 offset:54272
	ds_read_b128 v[222:225], v157 offset:55296
	ds_read_b128 v[226:229], v157 offset:56320
	global_load_lds_dwordx4 v[230:231], off
	v_lshl_add_u64 v[230:231], v[232:233], 0, s[36:37]
	s_add_i32 m0, s0, 0x2000
	s_add_i32 s0, s12, s17
	global_load_lds_dwordx4 v[230:231], off
	v_lshl_add_u64 v[230:231], v[234:235], 0, s[36:37]
	s_mov_b32 m0, s0
	s_nop 0
	global_load_lds_dwordx4 v[230:231], off
	v_lshl_add_u64 v[230:231], v[236:237], 0, s[36:37]
	s_add_i32 m0, s0, 0x2000
	s_nop 0
	global_load_lds_dwordx4 v[230:231], off
	v_lshl_add_u64 v[230:231], v[238:239], 0, s[36:37]
	s_mov_b32 m0, s10
	s_nop 0
	global_load_lds_dwordx4 v[230:231], off
	v_lshl_add_u64 v[230:231], v[240:241], 0, s[36:37]
	s_mov_b32 m0, s11
	s_nop 0
	global_load_lds_dwordx4 v[230:231], off
	s_waitcnt vmcnt(10)
	s_waitcnt lgkmcnt(0)
	s_barrier
	s_setprio 1
	s_waitcnt lgkmcnt(0)
	v_mfma_f32_16x16x32_bf16 v[52:55], v[128:131], v[178:181], v[52:55]
	v_mfma_f32_16x16x32_bf16 v[48:51], v[136:139], v[178:181], v[48:51]
	v_mfma_f32_16x16x32_bf16 v[36:39], v[128:131], v[206:209], v[36:39]
	v_mfma_f32_16x16x32_bf16 v[32:35], v[136:139], v[206:209], v[32:35]
	v_mfma_f32_16x16x32_bf16 v[20:23], v[128:131], v[214:217], v[20:23]
	v_mfma_f32_16x16x32_bf16 v[16:19], v[136:139], v[214:217], v[16:19]
	v_mfma_f32_16x16x32_bf16 v[4:7], v[128:131], v[222:225], v[4:7]
	v_mfma_f32_16x16x32_bf16 v[0:3], v[136:139], v[222:225], v[0:3]
	v_mfma_f32_16x16x32_bf16 v[52:55], v[132:135], v[202:205], v[52:55]
	v_mfma_f32_16x16x32_bf16 v[48:51], v[140:143], v[202:205], v[48:51]
	v_mfma_f32_16x16x32_bf16 v[36:39], v[132:135], v[210:213], v[36:39]
	v_mfma_f32_16x16x32_bf16 v[32:35], v[140:143], v[210:213], v[32:35]
	v_mfma_f32_16x16x32_bf16 v[20:23], v[132:135], v[218:221], v[20:23]
	v_mfma_f32_16x16x32_bf16 v[16:19], v[140:143], v[218:221], v[16:19]
	v_mfma_f32_16x16x32_bf16 v[4:7], v[132:135], v[226:229], v[4:7]
	v_mfma_f32_16x16x32_bf16 v[0:3], v[140:143], v[226:229], v[0:3]
	v_mfma_f32_16x16x32_bf16 v[60:63], v[144:147], v[178:181], v[60:63]
	v_mfma_f32_16x16x32_bf16 v[56:59], v[170:173], v[178:181], v[56:59]
	v_mfma_f32_16x16x32_bf16 v[44:47], v[144:147], v[206:209], v[44:47]
	v_mfma_f32_16x16x32_bf16 v[40:43], v[170:173], v[206:209], v[40:43]
	v_mfma_f32_16x16x32_bf16 v[28:31], v[144:147], v[214:217], v[28:31]
	v_mfma_f32_16x16x32_bf16 v[24:27], v[170:173], v[214:217], v[24:27]
	v_mfma_f32_16x16x32_bf16 v[12:15], v[144:147], v[222:225], v[12:15]
	v_mfma_f32_16x16x32_bf16 v[8:11], v[170:173], v[222:225], v[8:11]
	v_mfma_f32_16x16x32_bf16 v[60:63], v[148:151], v[202:205], v[60:63]
	v_mfma_f32_16x16x32_bf16 v[56:59], v[174:177], v[202:205], v[56:59]
	v_mfma_f32_16x16x32_bf16 v[44:47], v[148:151], v[210:213], v[44:47]
	v_mfma_f32_16x16x32_bf16 v[40:43], v[174:177], v[210:213], v[40:43]
	v_mfma_f32_16x16x32_bf16 v[28:31], v[148:151], v[218:221], v[28:31]
	v_mfma_f32_16x16x32_bf16 v[24:27], v[174:177], v[218:221], v[24:27]
	v_mfma_f32_16x16x32_bf16 v[12:15], v[148:151], v[226:229], v[12:15]
	v_mfma_f32_16x16x32_bf16 v[8:11], v[174:177], v[226:229], v[8:11]
	s_setprio 0
	s_barrier
	s_add_u32 s42, s42, 0x100
	s_addc_u32 s43, s43, 0
	s_add_u32 s46, s46, 0x100
	s_addc_u32 s47, s47, 0
	s_cmp_ge_u32 s97, s31
	s_mov_b32 s0, s97
.LBB0_375:
	s_nop 0
	s_add_i32 s97, s0, 2
	s_add_u32 s2, s42, 0x80
	s_addc_u32 s1, s43, 0
	s_add_i32 s12, 0, 0x10000
	s_cmp_eq_u32 s13, s0
	s_cselect_b32 s1, s95, s1
	s_cselect_b32 s0, s94, s2
	s_cselect_b32 s15, s55, s47
	s_cselect_b32 s14, s54, s46
	s_add_i32 s2, 0, 0x14000
	v_add_u32_e32 v140, s12, v195
	v_add_u32_e32 v174, s2, v195
	ds_read_b128 v[128:131], v140
	ds_read_b128 v[132:135], v140 offset:1024
	ds_read_b128 v[136:139], v140 offset:2048
	ds_read_b128 v[140:143], v140 offset:3072
	ds_read_b128 v[144:147], v174
	ds_read_b128 v[148:151], v174 offset:1024
	ds_read_b128 v[170:173], v174 offset:2048
	ds_read_b128 v[174:177], v174 offset:3072
	v_lshl_add_u64 v[230:231], s[42:43], 0, v[166:167]
	s_add_i32 m0, s45, 0xc000
	ds_read_b128 v[178:181], v157
	ds_read_b128 v[202:205], v157 offset:1024
	ds_read_b128 v[206:209], v157 offset:2048
	ds_read_b128 v[210:213], v157 offset:3072
	ds_read_b128 v[214:217], v157 offset:4096
	ds_read_b128 v[218:221], v157 offset:5120
	ds_read_b128 v[222:225], v157 offset:6144
	ds_read_b128 v[226:229], v157 offset:7168
	global_load_lds_dwordx4 v[230:231], off
	v_lshl_add_u64 v[230:231], s[42:43], 0, v[168:169]
	s_add_i32 m0, s45, 0xe000
	s_nop 0
	global_load_lds_dwordx4 v[230:231], off
	s_waitcnt vmcnt(8)
	s_waitcnt lgkmcnt(0)
	s_barrier
	s_setprio 1
	s_waitcnt lgkmcnt(0)
	v_mfma_f32_16x16x32_bf16 v[120:123], v[128:131], v[178:181], v[120:123]
	v_mfma_f32_16x16x32_bf16 v[124:127], v[136:139], v[178:181], v[124:127]
	v_mfma_f32_16x16x32_bf16 v[100:103], v[128:131], v[206:209], v[100:103]
	v_mfma_f32_16x16x32_bf16 v[96:99], v[136:139], v[206:209], v[96:99]
	v_mfma_f32_16x16x32_bf16 v[84:87], v[128:131], v[214:217], v[84:87]
	v_mfma_f32_16x16x32_bf16 v[80:83], v[136:139], v[214:217], v[80:83]
	v_mfma_f32_16x16x32_bf16 v[68:71], v[128:131], v[222:225], v[68:71]
	v_mfma_f32_16x16x32_bf16 v[64:67], v[136:139], v[222:225], v[64:67]
	v_mfma_f32_16x16x32_bf16 v[120:123], v[132:135], v[202:205], v[120:123]
	v_mfma_f32_16x16x32_bf16 v[124:127], v[140:143], v[202:205], v[124:127]
	v_mfma_f32_16x16x32_bf16 v[100:103], v[132:135], v[210:213], v[100:103]
	v_mfma_f32_16x16x32_bf16 v[96:99], v[140:143], v[210:213], v[96:99]
	v_mfma_f32_16x16x32_bf16 v[84:87], v[132:135], v[218:221], v[84:87]
	v_mfma_f32_16x16x32_bf16 v[80:83], v[140:143], v[218:221], v[80:83]
	v_mfma_f32_16x16x32_bf16 v[68:71], v[132:135], v[226:229], v[68:71]
	v_mfma_f32_16x16x32_bf16 v[64:67], v[140:143], v[226:229], v[64:67]
	v_mfma_f32_16x16x32_bf16 v[116:119], v[144:147], v[178:181], v[116:119]
	v_mfma_f32_16x16x32_bf16 v[112:115], v[170:173], v[178:181], v[112:115]
	v_mfma_f32_16x16x32_bf16 v[108:111], v[144:147], v[206:209], v[108:111]
	v_mfma_f32_16x16x32_bf16 v[104:107], v[170:173], v[206:209], v[104:107]
	v_mfma_f32_16x16x32_bf16 v[92:95], v[144:147], v[214:217], v[92:95]
	v_mfma_f32_16x16x32_bf16 v[88:91], v[170:173], v[214:217], v[88:91]
	v_mfma_f32_16x16x32_bf16 v[76:79], v[144:147], v[222:225], v[76:79]
	v_mfma_f32_16x16x32_bf16 v[72:75], v[170:173], v[222:225], v[72:75]
	v_mfma_f32_16x16x32_bf16 v[116:119], v[148:151], v[202:205], v[116:119]
	v_mfma_f32_16x16x32_bf16 v[112:115], v[174:177], v[202:205], v[112:115]
	v_mfma_f32_16x16x32_bf16 v[108:111], v[148:151], v[210:213], v[108:111]
	v_mfma_f32_16x16x32_bf16 v[104:107], v[174:177], v[210:213], v[104:107]
	v_mfma_f32_16x16x32_bf16 v[92:95], v[148:151], v[218:221], v[92:95]
	v_mfma_f32_16x16x32_bf16 v[88:91], v[174:177], v[218:221], v[88:91]
	v_mfma_f32_16x16x32_bf16 v[76:79], v[148:151], v[226:229], v[76:79]
	v_mfma_f32_16x16x32_bf16 v[72:75], v[174:177], v[226:229], v[72:75]
	s_setprio 0
	s_barrier
	s_add_i32 s12, s12, s17
	v_lshl_add_u64 v[230:231], s[14:15], 0, v[154:155]
	s_mov_b32 m0, s12
	ds_read_b128 v[178:181], v157 offset:16384
	ds_read_b128 v[202:205], v157 offset:17408
	ds_read_b128 v[206:209], v157 offset:18432
	ds_read_b128 v[210:213], v157 offset:19456
	ds_read_b128 v[214:217], v157 offset:20480
	ds_read_b128 v[218:221], v157 offset:21504
	ds_read_b128 v[222:225], v157 offset:22528
	ds_read_b128 v[226:229], v157 offset:23552
	global_load_lds_dwordx4 v[230:231], off
	s_add_i32 m0, s12, 0x2000
	v_lshl_add_u64 v[232:233], s[14:15], 0, v[162:163]
	s_add_u32 s14, s14, s24
	s_addc_u32 s15, s15, s25
	s_add_i32 s2, s2, s17
	global_load_lds_dwordx4 v[232:233], off
	v_lshl_add_u64 v[234:235], s[14:15], 0, v[154:155]
	s_mov_b32 m0, s2
	v_lshl_add_u64 v[236:237], s[14:15], 0, v[162:163]
	global_load_lds_dwordx4 v[234:235], off
	s_add_i32 m0, s2, 0x2000
	v_lshl_add_u64 v[238:239], s[0:1], 0, v[158:159]
	global_load_lds_dwordx4 v[236:237], off
	s_mov_b32 m0, s45
	v_lshl_add_u64 v[240:241], s[0:1], 0, v[160:161]
	global_load_lds_dwordx4 v[238:239], off
	s_mov_b32 m0, s83
	s_nop 0
	global_load_lds_dwordx4 v[240:241], off
	s_waitcnt vmcnt(8)
	s_waitcnt lgkmcnt(0)
	s_barrier
	s_setprio 1
	s_waitcnt lgkmcnt(0)
	v_mfma_f32_16x16x32_bf16 v[52:55], v[128:131], v[178:181], v[52:55]
	v_mfma_f32_16x16x32_bf16 v[48:51], v[136:139], v[178:181], v[48:51]
	v_mfma_f32_16x16x32_bf16 v[36:39], v[128:131], v[206:209], v[36:39]
	v_mfma_f32_16x16x32_bf16 v[32:35], v[136:139], v[206:209], v[32:35]
	v_mfma_f32_16x16x32_bf16 v[20:23], v[128:131], v[214:217], v[20:23]
	v_mfma_f32_16x16x32_bf16 v[16:19], v[136:139], v[214:217], v[16:19]
	v_mfma_f32_16x16x32_bf16 v[4:7], v[128:131], v[222:225], v[4:7]
	v_mfma_f32_16x16x32_bf16 v[0:3], v[136:139], v[222:225], v[0:3]
	v_mfma_f32_16x16x32_bf16 v[52:55], v[132:135], v[202:205], v[52:55]
	v_mfma_f32_16x16x32_bf16 v[48:51], v[140:143], v[202:205], v[48:51]
	v_mfma_f32_16x16x32_bf16 v[36:39], v[132:135], v[210:213], v[36:39]
	v_mfma_f32_16x16x32_bf16 v[32:35], v[140:143], v[210:213], v[32:35]
	v_mfma_f32_16x16x32_bf16 v[20:23], v[132:135], v[218:221], v[20:23]
	v_mfma_f32_16x16x32_bf16 v[16:19], v[140:143], v[218:221], v[16:19]
	v_mfma_f32_16x16x32_bf16 v[4:7], v[132:135], v[226:229], v[4:7]
	v_mfma_f32_16x16x32_bf16 v[0:3], v[140:143], v[226:229], v[0:3]
	v_mfma_f32_16x16x32_bf16 v[60:63], v[144:147], v[178:181], v[60:63]
	v_mfma_f32_16x16x32_bf16 v[56:59], v[170:173], v[178:181], v[56:59]
	v_mfma_f32_16x16x32_bf16 v[44:47], v[144:147], v[206:209], v[44:47]
	v_mfma_f32_16x16x32_bf16 v[40:43], v[170:173], v[206:209], v[40:43]
	v_mfma_f32_16x16x32_bf16 v[28:31], v[144:147], v[214:217], v[28:31]
	v_mfma_f32_16x16x32_bf16 v[24:27], v[170:173], v[214:217], v[24:27]
	v_mfma_f32_16x16x32_bf16 v[12:15], v[144:147], v[222:225], v[12:15]
	v_mfma_f32_16x16x32_bf16 v[8:11], v[170:173], v[222:225], v[8:11]
	v_mfma_f32_16x16x32_bf16 v[60:63], v[148:151], v[202:205], v[60:63]
	v_mfma_f32_16x16x32_bf16 v[56:59], v[174:177], v[202:205], v[56:59]
	v_mfma_f32_16x16x32_bf16 v[44:47], v[148:151], v[210:213], v[44:47]
	v_mfma_f32_16x16x32_bf16 v[40:43], v[174:177], v[210:213], v[40:43]
	v_mfma_f32_16x16x32_bf16 v[28:31], v[148:151], v[218:221], v[28:31]
	v_mfma_f32_16x16x32_bf16 v[24:27], v[174:177], v[218:221], v[24:27]
	v_mfma_f32_16x16x32_bf16 v[12:15], v[148:151], v[226:229], v[12:15]
	v_mfma_f32_16x16x32_bf16 v[8:11], v[174:177], v[226:229], v[8:11]
	s_setprio 0
	s_barrier
	s_add_i32 s2, 0, 0x18000
	s_add_i32 s12, 0, 0x1c000
	v_add_u32_e32 v140, s2, v195
	v_add_u32_e32 v174, s12, v195
	ds_read_b128 v[128:131], v140
	ds_read_b128 v[132:135], v140 offset:1024
	ds_read_b128 v[136:139], v140 offset:2048
	ds_read_b128 v[140:143], v140 offset:3072
	ds_read_b128 v[144:147], v174
	ds_read_b128 v[148:151], v174 offset:1024
	ds_read_b128 v[170:173], v174 offset:2048
	ds_read_b128 v[174:177], v174 offset:3072
	s_add_u32 s0, s0, s8
	s_addc_u32 s1, s1, s9
	s_mov_b32 m0, s28
	v_lshl_add_u64 v[242:243], s[0:1], 0, v[158:159]
	ds_read_b128 v[178:181], v157 offset:32768
	ds_read_b128 v[202:205], v157 offset:33792
	ds_read_b128 v[206:209], v157 offset:34816
	ds_read_b128 v[210:213], v157 offset:35840
	ds_read_b128 v[214:217], v157 offset:36864
	ds_read_b128 v[218:221], v157 offset:37888
	ds_read_b128 v[222:225], v157 offset:38912
	ds_read_b128 v[226:229], v157 offset:39936
	global_load_lds_dwordx4 v[242:243], off
	v_lshl_add_u64 v[242:243], s[0:1], 0, v[160:161]
	s_mov_b32 m0, s29
	s_nop 0
	global_load_lds_dwordx4 v[242:243], off
	s_waitcnt vmcnt(8)
	s_waitcnt lgkmcnt(0)
	s_barrier
	s_setprio 1
	s_waitcnt lgkmcnt(0)
	v_mfma_f32_16x16x32_bf16 v[120:123], v[128:131], v[178:181], v[120:123]
	v_mfma_f32_16x16x32_bf16 v[124:127], v[136:139], v[178:181], v[124:127]
	v_mfma_f32_16x16x32_bf16 v[100:103], v[128:131], v[206:209], v[100:103]
	v_mfma_f32_16x16x32_bf16 v[96:99], v[136:139], v[206:209], v[96:99]
	v_mfma_f32_16x16x32_bf16 v[84:87], v[128:131], v[214:217], v[84:87]
	v_mfma_f32_16x16x32_bf16 v[80:83], v[136:139], v[214:217], v[80:83]
	v_mfma_f32_16x16x32_bf16 v[68:71], v[128:131], v[222:225], v[68:71]
	v_mfma_f32_16x16x32_bf16 v[64:67], v[136:139], v[222:225], v[64:67]
	v_mfma_f32_16x16x32_bf16 v[120:123], v[132:135], v[202:205], v[120:123]
	v_mfma_f32_16x16x32_bf16 v[124:127], v[140:143], v[202:205], v[124:127]
	v_mfma_f32_16x16x32_bf16 v[100:103], v[132:135], v[210:213], v[100:103]
	v_mfma_f32_16x16x32_bf16 v[96:99], v[140:143], v[210:213], v[96:99]
	v_mfma_f32_16x16x32_bf16 v[84:87], v[132:135], v[218:221], v[84:87]
	v_mfma_f32_16x16x32_bf16 v[80:83], v[140:143], v[218:221], v[80:83]
	v_mfma_f32_16x16x32_bf16 v[68:71], v[132:135], v[226:229], v[68:71]
	v_mfma_f32_16x16x32_bf16 v[64:67], v[140:143], v[226:229], v[64:67]
	v_mfma_f32_16x16x32_bf16 v[116:119], v[144:147], v[178:181], v[116:119]
	v_mfma_f32_16x16x32_bf16 v[112:115], v[170:173], v[178:181], v[112:115]
	v_mfma_f32_16x16x32_bf16 v[108:111], v[144:147], v[206:209], v[108:111]
	v_mfma_f32_16x16x32_bf16 v[104:107], v[170:173], v[206:209], v[104:107]
	v_mfma_f32_16x16x32_bf16 v[92:95], v[144:147], v[214:217], v[92:95]
	v_mfma_f32_16x16x32_bf16 v[88:91], v[170:173], v[214:217], v[88:91]
	v_mfma_f32_16x16x32_bf16 v[76:79], v[144:147], v[222:225], v[76:79]
	v_mfma_f32_16x16x32_bf16 v[72:75], v[170:173], v[222:225], v[72:75]
	v_mfma_f32_16x16x32_bf16 v[116:119], v[148:151], v[202:205], v[116:119]
	v_mfma_f32_16x16x32_bf16 v[112:115], v[174:177], v[202:205], v[112:115]
	v_mfma_f32_16x16x32_bf16 v[108:111], v[148:151], v[210:213], v[108:111]
	v_mfma_f32_16x16x32_bf16 v[104:107], v[174:177], v[210:213], v[104:107]
	v_mfma_f32_16x16x32_bf16 v[92:95], v[148:151], v[218:221], v[92:95]
	v_mfma_f32_16x16x32_bf16 v[88:91], v[174:177], v[218:221], v[88:91]
	v_mfma_f32_16x16x32_bf16 v[76:79], v[148:151], v[226:229], v[76:79]
	v_mfma_f32_16x16x32_bf16 v[72:75], v[174:177], v[226:229], v[72:75]
	s_setprio 0
	s_barrier
	s_nop 0
	s_add_i32 s0, s2, s17
	v_lshl_add_u64 v[230:231], v[230:231], 0, s[36:37]
	s_mov_b32 m0, s0
	ds_read_b128 v[178:181], v157 offset:49152
	ds_read_b128 v[202:205], v157 offset:50176
	ds_read_b128 v[206:209], v157 offset:51200
	ds_read_b128 v[210:213], v157 offset:52224
	ds_read_b128 v[214:217], v157 offset:53248
	ds_read_b128 v[218:221], v157 offset:54272
	ds_read_b128 v[222:225], v157 offset:55296
	ds_read_b128 v[226:229], v157 offset:56320
	global_load_lds_dwordx4 v[230:231], off
	v_lshl_add_u64 v[230:231], v[232:233], 0, s[36:37]
	s_add_i32 m0, s0, 0x2000
	s_add_i32 s0, s12, s17
	global_load_lds_dwordx4 v[230:231], off
	v_lshl_add_u64 v[230:231], v[234:235], 0, s[36:37]
	s_mov_b32 m0, s0
	s_nop 0
	global_load_lds_dwordx4 v[230:231], off
	v_lshl_add_u64 v[230:231], v[236:237], 0, s[36:37]
	s_add_i32 m0, s0, 0x2000
	s_nop 0
	global_load_lds_dwordx4 v[230:231], off
	v_lshl_add_u64 v[230:231], v[238:239], 0, s[36:37]
	s_mov_b32 m0, s10
	s_nop 0
	global_load_lds_dwordx4 v[230:231], off
	v_lshl_add_u64 v[230:231], v[240:241], 0, s[36:37]
	s_mov_b32 m0, s11
	s_nop 0
	global_load_lds_dwordx4 v[230:231], off
	s_waitcnt vmcnt(8)
	s_waitcnt lgkmcnt(0)
	s_barrier
	s_setprio 1
	s_waitcnt lgkmcnt(0)
	v_mfma_f32_16x16x32_bf16 v[52:55], v[128:131], v[178:181], v[52:55]
	v_mfma_f32_16x16x32_bf16 v[48:51], v[136:139], v[178:181], v[48:51]
	v_mfma_f32_16x16x32_bf16 v[36:39], v[128:131], v[206:209], v[36:39]
	v_mfma_f32_16x16x32_bf16 v[32:35], v[136:139], v[206:209], v[32:35]
	v_mfma_f32_16x16x32_bf16 v[20:23], v[128:131], v[214:217], v[20:23]
	v_mfma_f32_16x16x32_bf16 v[16:19], v[136:139], v[214:217], v[16:19]
	v_mfma_f32_16x16x32_bf16 v[4:7], v[128:131], v[222:225], v[4:7]
	v_mfma_f32_16x16x32_bf16 v[0:3], v[136:139], v[222:225], v[0:3]
	v_mfma_f32_16x16x32_bf16 v[52:55], v[132:135], v[202:205], v[52:55]
	v_mfma_f32_16x16x32_bf16 v[48:51], v[140:143], v[202:205], v[48:51]
	v_mfma_f32_16x16x32_bf16 v[36:39], v[132:135], v[210:213], v[36:39]
	v_mfma_f32_16x16x32_bf16 v[32:35], v[140:143], v[210:213], v[32:35]
	v_mfma_f32_16x16x32_bf16 v[20:23], v[132:135], v[218:221], v[20:23]
	v_mfma_f32_16x16x32_bf16 v[16:19], v[140:143], v[218:221], v[16:19]
	v_mfma_f32_16x16x32_bf16 v[4:7], v[132:135], v[226:229], v[4:7]
	v_mfma_f32_16x16x32_bf16 v[0:3], v[140:143], v[226:229], v[0:3]
	v_mfma_f32_16x16x32_bf16 v[60:63], v[144:147], v[178:181], v[60:63]
	v_mfma_f32_16x16x32_bf16 v[56:59], v[170:173], v[178:181], v[56:59]
	v_mfma_f32_16x16x32_bf16 v[44:47], v[144:147], v[206:209], v[44:47]
	v_mfma_f32_16x16x32_bf16 v[40:43], v[170:173], v[206:209], v[40:43]
	v_mfma_f32_16x16x32_bf16 v[28:31], v[144:147], v[214:217], v[28:31]
	v_mfma_f32_16x16x32_bf16 v[24:27], v[170:173], v[214:217], v[24:27]
	v_mfma_f32_16x16x32_bf16 v[12:15], v[144:147], v[222:225], v[12:15]
	v_mfma_f32_16x16x32_bf16 v[8:11], v[170:173], v[222:225], v[8:11]
	v_mfma_f32_16x16x32_bf16 v[60:63], v[148:151], v[202:205], v[60:63]
	v_mfma_f32_16x16x32_bf16 v[56:59], v[174:177], v[202:205], v[56:59]
	v_mfma_f32_16x16x32_bf16 v[44:47], v[148:151], v[210:213], v[44:47]
	v_mfma_f32_16x16x32_bf16 v[40:43], v[174:177], v[210:213], v[40:43]
	v_mfma_f32_16x16x32_bf16 v[28:31], v[148:151], v[218:221], v[28:31]
	v_mfma_f32_16x16x32_bf16 v[24:27], v[174:177], v[218:221], v[24:27]
	v_mfma_f32_16x16x32_bf16 v[12:15], v[148:151], v[226:229], v[12:15]
	v_mfma_f32_16x16x32_bf16 v[8:11], v[174:177], v[226:229], v[8:11]
	s_setprio 0
	s_barrier
	s_add_u32 s42, s42, 0x100
	s_addc_u32 s43, s43, 0
	s_add_u32 s46, s46, 0x100
	s_addc_u32 s47, s47, 0
	s_cmp_ge_u32 s97, s31
	s_mov_b32 s0, s97
	s_cbranch_scc0 .LBB0_375
	s_and_b64 vcc, exec, s[74:75]
	s_cbranch_vccz .LBB0_378
	s_barrier

.Lpeel_join482_2:
	s_waitcnt lgkmcnt(0)
	s_barrier
	s_setprio 1
	s_waitcnt lgkmcnt(0)
	v_mfma_f32_16x16x32_bf16 v[60:63], v[128:131], v[202:205], 0
	v_mfma_f32_16x16x32_bf16 v[56:59], v[146:149], v[202:205], 0
	v_mfma_f32_16x16x32_bf16 v[44:47], v[128:131], v[210:213], 0
	v_mfma_f32_16x16x32_bf16 v[40:43], v[146:149], v[210:213], 0
	v_mfma_f32_16x16x32_bf16 v[28:31], v[128:131], v[218:221], 0
	v_mfma_f32_16x16x32_bf16 v[24:27], v[146:149], v[218:221], 0
	v_mfma_f32_16x16x32_bf16 v[12:15], v[128:131], v[226:229], 0
	v_mfma_f32_16x16x32_bf16 v[8:11], v[146:149], v[226:229], 0
	v_mfma_f32_16x16x32_bf16 v[60:63], v[132:135], v[206:209], v[60:63]
	v_mfma_f32_16x16x32_bf16 v[56:59], v[158:161], v[206:209], v[56:59]
	v_mfma_f32_16x16x32_bf16 v[44:47], v[132:135], v[214:217], v[44:47]
	v_mfma_f32_16x16x32_bf16 v[40:43], v[158:161], v[214:217], v[40:43]
	v_mfma_f32_16x16x32_bf16 v[28:31], v[132:135], v[222:225], v[28:31]
	v_mfma_f32_16x16x32_bf16 v[24:27], v[158:161], v[222:225], v[24:27]
	v_mfma_f32_16x16x32_bf16 v[12:15], v[132:135], v[230:233], v[12:15]
	v_mfma_f32_16x16x32_bf16 v[8:11], v[158:161], v[230:233], v[8:11]
	v_mfma_f32_16x16x32_bf16 v[52:55], v[168:171], v[202:205], 0
	v_mfma_f32_16x16x32_bf16 v[48:51], v[176:179], v[202:205], 0
	v_mfma_f32_16x16x32_bf16 v[36:39], v[168:171], v[210:213], 0
	v_mfma_f32_16x16x32_bf16 v[32:35], v[176:179], v[210:213], 0
	v_mfma_f32_16x16x32_bf16 v[20:23], v[168:171], v[218:221], 0
	v_mfma_f32_16x16x32_bf16 v[16:19], v[176:179], v[218:221], 0
	v_mfma_f32_16x16x32_bf16 v[4:7], v[168:171], v[226:229], 0
	v_mfma_f32_16x16x32_bf16 v[0:3], v[176:179], v[226:229], 0
	v_mfma_f32_16x16x32_bf16 v[52:55], v[172:175], v[206:209], v[52:55]
	v_mfma_f32_16x16x32_bf16 v[48:51], v[194:197], v[206:209], v[48:51]
	v_mfma_f32_16x16x32_bf16 v[36:39], v[172:175], v[214:217], v[36:39]
	v_mfma_f32_16x16x32_bf16 v[32:35], v[194:197], v[214:217], v[32:35]
	v_mfma_f32_16x16x32_bf16 v[20:23], v[172:175], v[222:225], v[20:23]
	v_mfma_f32_16x16x32_bf16 v[16:19], v[194:197], v[222:225], v[16:19]
	v_mfma_f32_16x16x32_bf16 v[4:7], v[172:175], v[230:233], v[4:7]
	v_mfma_f32_16x16x32_bf16 v[0:3], v[194:197], v[230:233], v[0:3]
	s_setprio 0
	s_barrier
	s_add_i32 s14, 0, 0x18000
	s_add_i32 s15, 0, 0x1c000
	v_add_u32_e32 v158, s14, v165
	v_add_u32_e32 v193, s15, v165
	ds_read_b128 v[128:131], v158
	ds_read_b128 v[132:135], v158 offset:1024
	ds_read_b128 v[146:149], v158 offset:2048
	ds_read_b128 v[158:161], v158 offset:3072
	ds_read_b128 v[168:171], v193
	ds_read_b128 v[172:175], v193 offset:1024
	ds_read_b128 v[176:179], v193 offset:2048
	ds_read_b128 v[194:197], v193 offset:3072
	s_add_u32 s0, s0, s8
	s_addc_u32 s1, s1, s9
	s_mov_b32 m0, s11
	v_lshl_add_u64 v[240:241], s[0:1], 0, v[136:137]
	ds_read_b128 v[202:205], v167 offset:32768
	ds_read_b128 v[206:209], v167 offset:33792
	ds_read_b128 v[210:213], v167 offset:34816
	ds_read_b128 v[214:217], v167 offset:35840
	ds_read_b128 v[218:221], v167 offset:36864
	ds_read_b128 v[222:225], v167 offset:37888
	ds_read_b128 v[226:229], v167 offset:38912
	ds_read_b128 v[230:233], v167 offset:39936
	global_load_lds_dwordx4 v[240:241], off
	v_lshl_add_u64 v[240:241], s[0:1], 0, v[138:139]
	s_mov_b32 m0, s13
	s_nop 0
	global_load_lds_dwordx4 v[240:241], off
	s_waitcnt vmcnt(8)
	s_waitcnt lgkmcnt(0)
	s_barrier
	s_setprio 1
	s_waitcnt lgkmcnt(0)
	v_mfma_f32_16x16x32_bf16 v[124:127], v[128:131], v[202:205], v[124:127]
	v_mfma_f32_16x16x32_bf16 v[120:123], v[146:149], v[202:205], v[120:123]
	v_mfma_f32_16x16x32_bf16 v[108:111], v[128:131], v[210:213], v[108:111]
	v_mfma_f32_16x16x32_bf16 v[104:107], v[146:149], v[210:213], v[104:107]
	v_mfma_f32_16x16x32_bf16 v[92:95], v[128:131], v[218:221], v[92:95]
	v_mfma_f32_16x16x32_bf16 v[88:91], v[146:149], v[218:221], v[88:91]
	v_mfma_f32_16x16x32_bf16 v[76:79], v[128:131], v[226:229], v[76:79]
	v_mfma_f32_16x16x32_bf16 v[72:75], v[146:149], v[226:229], v[72:75]
	v_mfma_f32_16x16x32_bf16 v[124:127], v[132:135], v[206:209], v[124:127]
	v_mfma_f32_16x16x32_bf16 v[120:123], v[158:161], v[206:209], v[120:123]
	v_mfma_f32_16x16x32_bf16 v[108:111], v[132:135], v[214:217], v[108:111]
	v_mfma_f32_16x16x32_bf16 v[104:107], v[158:161], v[214:217], v[104:107]
	v_mfma_f32_16x16x32_bf16 v[92:95], v[132:135], v[222:225], v[92:95]
	v_mfma_f32_16x16x32_bf16 v[88:91], v[158:161], v[222:225], v[88:91]
	v_mfma_f32_16x16x32_bf16 v[76:79], v[132:135], v[230:233], v[76:79]
	v_mfma_f32_16x16x32_bf16 v[72:75], v[158:161], v[230:233], v[72:75]
	v_mfma_f32_16x16x32_bf16 v[116:119], v[168:171], v[202:205], v[116:119]
	v_mfma_f32_16x16x32_bf16 v[112:115], v[176:179], v[202:205], v[112:115]
	v_mfma_f32_16x16x32_bf16 v[100:103], v[168:171], v[210:213], v[100:103]
	v_mfma_f32_16x16x32_bf16 v[96:99], v[176:179], v[210:213], v[96:99]
	v_mfma_f32_16x16x32_bf16 v[84:87], v[168:171], v[218:221], v[84:87]
	v_mfma_f32_16x16x32_bf16 v[80:83], v[176:179], v[218:221], v[80:83]
	v_mfma_f32_16x16x32_bf16 v[68:71], v[168:171], v[226:229], v[68:71]
	v_mfma_f32_16x16x32_bf16 v[64:67], v[176:179], v[226:229], v[64:67]
	v_mfma_f32_16x16x32_bf16 v[116:119], v[172:175], v[206:209], v[116:119]
	v_mfma_f32_16x16x32_bf16 v[112:115], v[194:197], v[206:209], v[112:115]
	v_mfma_f32_16x16x32_bf16 v[100:103], v[172:175], v[214:217], v[100:103]
	v_mfma_f32_16x16x32_bf16 v[96:99], v[194:197], v[214:217], v[96:99]
	v_mfma_f32_16x16x32_bf16 v[84:87], v[172:175], v[222:225], v[84:87]
	v_mfma_f32_16x16x32_bf16 v[80:83], v[194:197], v[222:225], v[80:83]
	v_mfma_f32_16x16x32_bf16 v[68:71], v[172:175], v[230:233], v[68:71]
	v_mfma_f32_16x16x32_bf16 v[64:67], v[194:197], v[230:233], v[64:67]
	s_setprio 0
	s_barrier
	s_nop 0
	s_add_i32 s0, s14, s2
	v_lshl_add_u64 v[150:151], v[150:151], 0, s[36:37]
	s_mov_b32 m0, s0
	ds_read_b128 v[202:205], v167 offset:49152
	ds_read_b128 v[206:209], v167 offset:50176
	ds_read_b128 v[210:213], v167 offset:51200
	ds_read_b128 v[214:217], v167 offset:52224
	ds_read_b128 v[218:221], v167 offset:53248
	ds_read_b128 v[222:225], v167 offset:54272
	ds_read_b128 v[226:229], v167 offset:55296
	ds_read_b128 v[230:233], v167 offset:56320
	global_load_lds_dwordx4 v[150:151], off
	v_lshl_add_u64 v[150:151], v[162:163], 0, s[36:37]
	s_add_i32 m0, s0, 0x2000
	s_add_i32 s0, s15, s2
	global_load_lds_dwordx4 v[150:151], off
	v_lshl_add_u64 v[150:151], v[180:181], 0, s[36:37]
	s_mov_b32 m0, s0
	s_nop 0
	global_load_lds_dwordx4 v[150:151], off
	v_lshl_add_u64 v[150:151], v[234:235], 0, s[36:37]
	s_add_i32 m0, s0, 0x2000
	s_nop 0
	global_load_lds_dwordx4 v[150:151], off
	v_lshl_add_u64 v[150:151], v[236:237], 0, s[36:37]
	s_mov_b32 m0, s18
	s_nop 0
	global_load_lds_dwordx4 v[150:151], off
	v_lshl_add_u64 v[150:151], v[238:239], 0, s[36:37]
	s_mov_b32 m0, s28
	s_nop 0
	global_load_lds_dwordx4 v[150:151], off
	s_waitcnt vmcnt(8)
	s_waitcnt lgkmcnt(0)
	s_barrier
	s_setprio 1
	s_waitcnt lgkmcnt(0)
	v_mfma_f32_16x16x32_bf16 v[60:63], v[128:131], v[202:205], v[60:63]
	v_mfma_f32_16x16x32_bf16 v[56:59], v[146:149], v[202:205], v[56:59]
	v_mfma_f32_16x16x32_bf16 v[44:47], v[128:131], v[210:213], v[44:47]
	v_mfma_f32_16x16x32_bf16 v[40:43], v[146:149], v[210:213], v[40:43]
	v_mfma_f32_16x16x32_bf16 v[28:31], v[128:131], v[218:221], v[28:31]
	v_mfma_f32_16x16x32_bf16 v[24:27], v[146:149], v[218:221], v[24:27]
	v_mfma_f32_16x16x32_bf16 v[12:15], v[128:131], v[226:229], v[12:15]
	v_mfma_f32_16x16x32_bf16 v[8:11], v[146:149], v[226:229], v[8:11]
	v_mfma_f32_16x16x32_bf16 v[60:63], v[132:135], v[206:209], v[60:63]
	v_mfma_f32_16x16x32_bf16 v[56:59], v[158:161], v[206:209], v[56:59]
	v_mfma_f32_16x16x32_bf16 v[44:47], v[132:135], v[214:217], v[44:47]
	v_mfma_f32_16x16x32_bf16 v[40:43], v[158:161], v[214:217], v[40:43]
	v_mfma_f32_16x16x32_bf16 v[28:31], v[132:135], v[222:225], v[28:31]
	v_mfma_f32_16x16x32_bf16 v[24:27], v[158:161], v[222:225], v[24:27]
	v_mfma_f32_16x16x32_bf16 v[12:15], v[132:135], v[230:233], v[12:15]
	v_mfma_f32_16x16x32_bf16 v[8:11], v[158:161], v[230:233], v[8:11]
	v_mfma_f32_16x16x32_bf16 v[52:55], v[168:171], v[202:205], v[52:55]
	v_mfma_f32_16x16x32_bf16 v[48:51], v[176:179], v[202:205], v[48:51]
	v_mfma_f32_16x16x32_bf16 v[36:39], v[168:171], v[210:213], v[36:39]
	v_mfma_f32_16x16x32_bf16 v[32:35], v[176:179], v[210:213], v[32:35]
	v_mfma_f32_16x16x32_bf16 v[20:23], v[168:171], v[218:221], v[20:23]
	v_mfma_f32_16x16x32_bf16 v[16:19], v[176:179], v[218:221], v[16:19]
	v_mfma_f32_16x16x32_bf16 v[4:7], v[168:171], v[226:229], v[4:7]
	v_mfma_f32_16x16x32_bf16 v[0:3], v[176:179], v[226:229], v[0:3]
	v_mfma_f32_16x16x32_bf16 v[52:55], v[172:175], v[206:209], v[52:55]
	v_mfma_f32_16x16x32_bf16 v[48:51], v[194:197], v[206:209], v[48:51]
	v_mfma_f32_16x16x32_bf16 v[36:39], v[172:175], v[214:217], v[36:39]
	v_mfma_f32_16x16x32_bf16 v[32:35], v[194:197], v[214:217], v[32:35]
	v_mfma_f32_16x16x32_bf16 v[20:23], v[172:175], v[222:225], v[20:23]
	v_mfma_f32_16x16x32_bf16 v[16:19], v[194:197], v[222:225], v[16:19]
	v_mfma_f32_16x16x32_bf16 v[4:7], v[172:175], v[230:233], v[4:7]
	v_mfma_f32_16x16x32_bf16 v[0:3], v[194:197], v[230:233], v[0:3]
	s_setprio 0
	s_barrier
	s_add_u32 s42, s42, 0x100
	s_addc_u32 s43, s43, 0
	s_add_u32 s44, s44, 0x100
	s_addc_u32 s45, s45, 0
	s_cmp_ge_u32 s47, s31
	s_mov_b32 s0, s47
.LBB0_482:
	s_nop 0
	s_add_i32 s47, s0, 2
	s_add_u32 s14, s42, 0x80
	s_addc_u32 s1, s43, 0
	s_add_i32 s15, 0, 0x10000
	s_cmp_eq_u32 s29, s0
	s_cselect_b32 s1, s77, s1
	s_cselect_b32 s0, s76, s14
	v_add_u32_e32 v150, s15, v165
	s_cselect_b32 s83, s79, s45
	s_cselect_b32 s82, s78, s44
	s_add_i32 s14, 0, 0x14000
	ds_read_b128 v[128:131], v150
	ds_read_b128 v[132:135], v150 offset:1024
	ds_read_b128 v[146:149], v150 offset:2048
	ds_read_b128 v[158:161], v150 offset:3072
	v_add_u32_e32 v150, s14, v165
	ds_read_b128 v[168:171], v150
	ds_read_b128 v[172:175], v150 offset:1024
	ds_read_b128 v[176:179], v150 offset:2048
	ds_read_b128 v[194:197], v150 offset:3072
	v_lshl_add_u64 v[150:151], s[42:43], 0, v[142:143]
	s_add_i32 m0, s3, 0xc000
	ds_read_b128 v[202:205], v167
	ds_read_b128 v[206:209], v167 offset:1024
	ds_read_b128 v[210:213], v167 offset:2048
	ds_read_b128 v[214:217], v167 offset:3072
	ds_read_b128 v[218:221], v167 offset:4096
	ds_read_b128 v[222:225], v167 offset:5120
	ds_read_b128 v[226:229], v167 offset:6144
	ds_read_b128 v[230:233], v167 offset:7168
	global_load_lds_dwordx4 v[150:151], off
	v_lshl_add_u64 v[150:151], s[42:43], 0, v[144:145]
	s_add_i32 m0, s3, 0xe000
	s_nop 0
	global_load_lds_dwordx4 v[150:151], off
	s_waitcnt vmcnt(8)
	s_waitcnt lgkmcnt(0)
	s_barrier
	s_setprio 1
	s_waitcnt lgkmcnt(0)
	v_mfma_f32_16x16x32_bf16 v[124:127], v[128:131], v[202:205], v[124:127]
	v_mfma_f32_16x16x32_bf16 v[120:123], v[146:149], v[202:205], v[120:123]
	v_mfma_f32_16x16x32_bf16 v[108:111], v[128:131], v[210:213], v[108:111]
	v_mfma_f32_16x16x32_bf16 v[104:107], v[146:149], v[210:213], v[104:107]
	v_mfma_f32_16x16x32_bf16 v[92:95], v[128:131], v[218:221], v[92:95]
	v_mfma_f32_16x16x32_bf16 v[88:91], v[146:149], v[218:221], v[88:91]
	v_mfma_f32_16x16x32_bf16 v[76:79], v[128:131], v[226:229], v[76:79]
	v_mfma_f32_16x16x32_bf16 v[72:75], v[146:149], v[226:229], v[72:75]
	v_mfma_f32_16x16x32_bf16 v[124:127], v[132:135], v[206:209], v[124:127]
	v_mfma_f32_16x16x32_bf16 v[120:123], v[158:161], v[206:209], v[120:123]
	v_mfma_f32_16x16x32_bf16 v[108:111], v[132:135], v[214:217], v[108:111]
	v_mfma_f32_16x16x32_bf16 v[104:107], v[158:161], v[214:217], v[104:107]
	v_mfma_f32_16x16x32_bf16 v[92:95], v[132:135], v[222:225], v[92:95]
	v_mfma_f32_16x16x32_bf16 v[88:91], v[158:161], v[222:225], v[88:91]
	v_mfma_f32_16x16x32_bf16 v[76:79], v[132:135], v[230:233], v[76:79]
	v_mfma_f32_16x16x32_bf16 v[72:75], v[158:161], v[230:233], v[72:75]
	v_mfma_f32_16x16x32_bf16 v[116:119], v[168:171], v[202:205], v[116:119]
	v_mfma_f32_16x16x32_bf16 v[112:115], v[176:179], v[202:205], v[112:115]
	v_mfma_f32_16x16x32_bf16 v[100:103], v[168:171], v[210:213], v[100:103]
	v_mfma_f32_16x16x32_bf16 v[96:99], v[176:179], v[210:213], v[96:99]
	v_mfma_f32_16x16x32_bf16 v[84:87], v[168:171], v[218:221], v[84:87]
	v_mfma_f32_16x16x32_bf16 v[80:83], v[176:179], v[218:221], v[80:83]
	v_mfma_f32_16x16x32_bf16 v[68:71], v[168:171], v[226:229], v[68:71]
	v_mfma_f32_16x16x32_bf16 v[64:67], v[176:179], v[226:229], v[64:67]
	v_mfma_f32_16x16x32_bf16 v[116:119], v[172:175], v[206:209], v[116:119]
	v_mfma_f32_16x16x32_bf16 v[112:115], v[194:197], v[206:209], v[112:115]
	v_mfma_f32_16x16x32_bf16 v[100:103], v[172:175], v[214:217], v[100:103]
	v_mfma_f32_16x16x32_bf16 v[96:99], v[194:197], v[214:217], v[96:99]
	v_mfma_f32_16x16x32_bf16 v[84:87], v[172:175], v[222:225], v[84:87]
	v_mfma_f32_16x16x32_bf16 v[80:83], v[194:197], v[222:225], v[80:83]
	v_mfma_f32_16x16x32_bf16 v[68:71], v[172:175], v[230:233], v[68:71]
	v_mfma_f32_16x16x32_bf16 v[64:67], v[194:197], v[230:233], v[64:67]
	s_setprio 0
	s_barrier
	s_add_i32 s15, s15, s2
	v_lshl_add_u64 v[150:151], s[82:83], 0, v[154:155]
	s_mov_b32 m0, s15
	ds_read_b128 v[202:205], v167 offset:16384
	ds_read_b128 v[206:209], v167 offset:17408
	ds_read_b128 v[210:213], v167 offset:18432
	ds_read_b128 v[214:217], v167 offset:19456
	ds_read_b128 v[218:221], v167 offset:20480
	ds_read_b128 v[222:225], v167 offset:21504
	ds_read_b128 v[226:229], v167 offset:22528
	ds_read_b128 v[230:233], v167 offset:23552
	global_load_lds_dwordx4 v[150:151], off
	s_add_i32 m0, s15, 0x2000
	v_lshl_add_u64 v[162:163], s[82:83], 0, v[140:141]
	s_add_u32 s82, s82, s24
	s_addc_u32 s83, s83, s25
	s_add_i32 s14, s14, s2
	global_load_lds_dwordx4 v[162:163], off
	v_lshl_add_u64 v[180:181], s[82:83], 0, v[154:155]
	s_mov_b32 m0, s14
	v_lshl_add_u64 v[234:235], s[82:83], 0, v[140:141]
	global_load_lds_dwordx4 v[180:181], off
	s_add_i32 m0, s14, 0x2000
	v_lshl_add_u64 v[236:237], s[0:1], 0, v[136:137]
	global_load_lds_dwordx4 v[234:235], off
	s_mov_b32 m0, s3
	v_lshl_add_u64 v[238:239], s[0:1], 0, v[138:139]
	global_load_lds_dwordx4 v[236:237], off
	s_mov_b32 m0, s10
	s_nop 0
	global_load_lds_dwordx4 v[238:239], off
	s_waitcnt vmcnt(8)
	s_waitcnt lgkmcnt(0)
	s_barrier
	s_setprio 1
	s_waitcnt lgkmcnt(0)
	v_mfma_f32_16x16x32_bf16 v[60:63], v[128:131], v[202:205], v[60:63]
	v_mfma_f32_16x16x32_bf16 v[56:59], v[146:149], v[202:205], v[56:59]
	v_mfma_f32_16x16x32_bf16 v[44:47], v[128:131], v[210:213], v[44:47]
	v_mfma_f32_16x16x32_bf16 v[40:43], v[146:149], v[210:213], v[40:43]
	v_mfma_f32_16x16x32_bf16 v[28:31], v[128:131], v[218:221], v[28:31]
	v_mfma_f32_16x16x32_bf16 v[24:27], v[146:149], v[218:221], v[24:27]
	v_mfma_f32_16x16x32_bf16 v[12:15], v[128:131], v[226:229], v[12:15]
	v_mfma_f32_16x16x32_bf16 v[8:11], v[146:149], v[226:229], v[8:11]
	v_mfma_f32_16x16x32_bf16 v[60:63], v[132:135], v[206:209], v[60:63]
	v_mfma_f32_16x16x32_bf16 v[56:59], v[158:161], v[206:209], v[56:59]
	v_mfma_f32_16x16x32_bf16 v[44:47], v[132:135], v[214:217], v[44:47]
	v_mfma_f32_16x16x32_bf16 v[40:43], v[158:161], v[214:217], v[40:43]
	v_mfma_f32_16x16x32_bf16 v[28:31], v[132:135], v[222:225], v[28:31]
	v_mfma_f32_16x16x32_bf16 v[24:27], v[158:161], v[222:225], v[24:27]
	v_mfma_f32_16x16x32_bf16 v[12:15], v[132:135], v[230:233], v[12:15]
	v_mfma_f32_16x16x32_bf16 v[8:11], v[158:161], v[230:233], v[8:11]
	v_mfma_f32_16x16x32_bf16 v[52:55], v[168:171], v[202:205], v[52:55]
	v_mfma_f32_16x16x32_bf16 v[48:51], v[176:179], v[202:205], v[48:51]
	v_mfma_f32_16x16x32_bf16 v[36:39], v[168:171], v[210:213], v[36:39]
	v_mfma_f32_16x16x32_bf16 v[32:35], v[176:179], v[210:213], v[32:35]
	v_mfma_f32_16x16x32_bf16 v[20:23], v[168:171], v[218:221], v[20:23]
	v_mfma_f32_16x16x32_bf16 v[16:19], v[176:179], v[218:221], v[16:19]
	v_mfma_f32_16x16x32_bf16 v[4:7], v[168:171], v[226:229], v[4:7]
	v_mfma_f32_16x16x32_bf16 v[0:3], v[176:179], v[226:229], v[0:3]
	v_mfma_f32_16x16x32_bf16 v[52:55], v[172:175], v[206:209], v[52:55]
	v_mfma_f32_16x16x32_bf16 v[48:51], v[194:197], v[206:209], v[48:51]
	v_mfma_f32_16x16x32_bf16 v[36:39], v[172:175], v[214:217], v[36:39]
	v_mfma_f32_16x16x32_bf16 v[32:35], v[194:197], v[214:217], v[32:35]
	v_mfma_f32_16x16x32_bf16 v[20:23], v[172:175], v[222:225], v[20:23]
	v_mfma_f32_16x16x32_bf16 v[16:19], v[194:197], v[222:225], v[16:19]
	v_mfma_f32_16x16x32_bf16 v[4:7], v[172:175], v[230:233], v[4:7]
	v_mfma_f32_16x16x32_bf16 v[0:3], v[194:197], v[230:233], v[0:3]
	s_setprio 0
	s_barrier
	s_add_i32 s14, 0, 0x18000
	s_add_i32 s15, 0, 0x1c000
	v_add_u32_e32 v158, s14, v165
	v_add_u32_e32 v193, s15, v165
	ds_read_b128 v[128:131], v158
	ds_read_b128 v[132:135], v158 offset:1024
	ds_read_b128 v[146:149], v158 offset:2048
	ds_read_b128 v[158:161], v158 offset:3072
	ds_read_b128 v[168:171], v193
	ds_read_b128 v[172:175], v193 offset:1024
	ds_read_b128 v[176:179], v193 offset:2048
	ds_read_b128 v[194:197], v193 offset:3072
	s_add_u32 s0, s0, s8
	s_addc_u32 s1, s1, s9
	s_mov_b32 m0, s11
	v_lshl_add_u64 v[240:241], s[0:1], 0, v[136:137]
	ds_read_b128 v[202:205], v167 offset:32768
	ds_read_b128 v[206:209], v167 offset:33792
	ds_read_b128 v[210:213], v167 offset:34816
	ds_read_b128 v[214:217], v167 offset:35840
	ds_read_b128 v[218:221], v167 offset:36864
	ds_read_b128 v[222:225], v167 offset:37888
	ds_read_b128 v[226:229], v167 offset:38912
	ds_read_b128 v[230:233], v167 offset:39936
	global_load_lds_dwordx4 v[240:241], off
	v_lshl_add_u64 v[240:241], s[0:1], 0, v[138:139]
	s_mov_b32 m0, s13
	s_nop 0
	global_load_lds_dwordx4 v[240:241], off
	s_waitcnt vmcnt(8)
	s_waitcnt lgkmcnt(0)
	s_barrier
	s_setprio 1
	s_waitcnt lgkmcnt(0)
	v_mfma_f32_16x16x32_bf16 v[124:127], v[128:131], v[202:205], v[124:127]
	v_mfma_f32_16x16x32_bf16 v[120:123], v[146:149], v[202:205], v[120:123]
	v_mfma_f32_16x16x32_bf16 v[108:111], v[128:131], v[210:213], v[108:111]
	v_mfma_f32_16x16x32_bf16 v[104:107], v[146:149], v[210:213], v[104:107]
	v_mfma_f32_16x16x32_bf16 v[92:95], v[128:131], v[218:221], v[92:95]
	v_mfma_f32_16x16x32_bf16 v[88:91], v[146:149], v[218:221], v[88:91]
	v_mfma_f32_16x16x32_bf16 v[76:79], v[128:131], v[226:229], v[76:79]
	v_mfma_f32_16x16x32_bf16 v[72:75], v[146:149], v[226:229], v[72:75]
	v_mfma_f32_16x16x32_bf16 v[124:127], v[132:135], v[206:209], v[124:127]
	v_mfma_f32_16x16x32_bf16 v[120:123], v[158:161], v[206:209], v[120:123]
	v_mfma_f32_16x16x32_bf16 v[108:111], v[132:135], v[214:217], v[108:111]
	v_mfma_f32_16x16x32_bf16 v[104:107], v[158:161], v[214:217], v[104:107]
	v_mfma_f32_16x16x32_bf16 v[92:95], v[132:135], v[222:225], v[92:95]
	v_mfma_f32_16x16x32_bf16 v[88:91], v[158:161], v[222:225], v[88:91]
	v_mfma_f32_16x16x32_bf16 v[76:79], v[132:135], v[230:233], v[76:79]
	v_mfma_f32_16x16x32_bf16 v[72:75], v[158:161], v[230:233], v[72:75]
	v_mfma_f32_16x16x32_bf16 v[116:119], v[168:171], v[202:205], v[116:119]
	v_mfma_f32_16x16x32_bf16 v[112:115], v[176:179], v[202:205], v[112:115]
	v_mfma_f32_16x16x32_bf16 v[100:103], v[168:171], v[210:213], v[100:103]
	v_mfma_f32_16x16x32_bf16 v[96:99], v[176:179], v[210:213], v[96:99]
	v_mfma_f32_16x16x32_bf16 v[84:87], v[168:171], v[218:221], v[84:87]
	v_mfma_f32_16x16x32_bf16 v[80:83], v[176:179], v[218:221], v[80:83]
	v_mfma_f32_16x16x32_bf16 v[68:71], v[168:171], v[226:229], v[68:71]
	v_mfma_f32_16x16x32_bf16 v[64:67], v[176:179], v[226:229], v[64:67]
	v_mfma_f32_16x16x32_bf16 v[116:119], v[172:175], v[206:209], v[116:119]
	v_mfma_f32_16x16x32_bf16 v[112:115], v[194:197], v[206:209], v[112:115]
	v_mfma_f32_16x16x32_bf16 v[100:103], v[172:175], v[214:217], v[100:103]
	v_mfma_f32_16x16x32_bf16 v[96:99], v[194:197], v[214:217], v[96:99]
	v_mfma_f32_16x16x32_bf16 v[84:87], v[172:175], v[222:225], v[84:87]
	v_mfma_f32_16x16x32_bf16 v[80:83], v[194:197], v[222:225], v[80:83]
	v_mfma_f32_16x16x32_bf16 v[68:71], v[172:175], v[230:233], v[68:71]
	v_mfma_f32_16x16x32_bf16 v[64:67], v[194:197], v[230:233], v[64:67]
	s_setprio 0
	s_barrier
	s_nop 0
	s_add_i32 s0, s14, s2
	v_lshl_add_u64 v[150:151], v[150:151], 0, s[36:37]
	s_mov_b32 m0, s0
	ds_read_b128 v[202:205], v167 offset:49152
	ds_read_b128 v[206:209], v167 offset:50176
	ds_read_b128 v[210:213], v167 offset:51200
	ds_read_b128 v[214:217], v167 offset:52224
	ds_read_b128 v[218:221], v167 offset:53248
	ds_read_b128 v[222:225], v167 offset:54272
	ds_read_b128 v[226:229], v167 offset:55296
	ds_read_b128 v[230:233], v167 offset:56320
	global_load_lds_dwordx4 v[150:151], off
	v_lshl_add_u64 v[150:151], v[162:163], 0, s[36:37]
	s_add_i32 m0, s0, 0x2000
	s_add_i32 s0, s15, s2
	global_load_lds_dwordx4 v[150:151], off
	v_lshl_add_u64 v[150:151], v[180:181], 0, s[36:37]
	s_mov_b32 m0, s0
	s_nop 0
	global_load_lds_dwordx4 v[150:151], off
	v_lshl_add_u64 v[150:151], v[234:235], 0, s[36:37]
	s_add_i32 m0, s0, 0x2000
	s_nop 0
	global_load_lds_dwordx4 v[150:151], off
	v_lshl_add_u64 v[150:151], v[236:237], 0, s[36:37]
	s_mov_b32 m0, s18
	s_nop 0
	global_load_lds_dwordx4 v[150:151], off
	v_lshl_add_u64 v[150:151], v[238:239], 0, s[36:37]
	s_mov_b32 m0, s28
	s_nop 0
	global_load_lds_dwordx4 v[150:151], off
	s_waitcnt vmcnt(8)
	s_waitcnt lgkmcnt(0)
	s_barrier
	s_setprio 1
	s_waitcnt lgkmcnt(0)
	v_mfma_f32_16x16x32_bf16 v[60:63], v[128:131], v[202:205], v[60:63]
	v_mfma_f32_16x16x32_bf16 v[56:59], v[146:149], v[202:205], v[56:59]
	v_mfma_f32_16x16x32_bf16 v[44:47], v[128:131], v[210:213], v[44:47]
	v_mfma_f32_16x16x32_bf16 v[40:43], v[146:149], v[210:213], v[40:43]
	v_mfma_f32_16x16x32_bf16 v[28:31], v[128:131], v[218:221], v[28:31]
	v_mfma_f32_16x16x32_bf16 v[24:27], v[146:149], v[218:221], v[24:27]
	v_mfma_f32_16x16x32_bf16 v[12:15], v[128:131], v[226:229], v[12:15]
	v_mfma_f32_16x16x32_bf16 v[8:11], v[146:149], v[226:229], v[8:11]
	v_mfma_f32_16x16x32_bf16 v[60:63], v[132:135], v[206:209], v[60:63]
	v_mfma_f32_16x16x32_bf16 v[56:59], v[158:161], v[206:209], v[56:59]
	v_mfma_f32_16x16x32_bf16 v[44:47], v[132:135], v[214:217], v[44:47]
	v_mfma_f32_16x16x32_bf16 v[40:43], v[158:161], v[214:217], v[40:43]
	v_mfma_f32_16x16x32_bf16 v[28:31], v[132:135], v[222:225], v[28:31]
	v_mfma_f32_16x16x32_bf16 v[24:27], v[158:161], v[222:225], v[24:27]
	v_mfma_f32_16x16x32_bf16 v[12:15], v[132:135], v[230:233], v[12:15]
	v_mfma_f32_16x16x32_bf16 v[8:11], v[158:161], v[230:233], v[8:11]
	v_mfma_f32_16x16x32_bf16 v[52:55], v[168:171], v[202:205], v[52:55]
	v_mfma_f32_16x16x32_bf16 v[48:51], v[176:179], v[202:205], v[48:51]
	v_mfma_f32_16x16x32_bf16 v[36:39], v[168:171], v[210:213], v[36:39]
	v_mfma_f32_16x16x32_bf16 v[32:35], v[176:179], v[210:213], v[32:35]
	v_mfma_f32_16x16x32_bf16 v[20:23], v[168:171], v[218:221], v[20:23]
	v_mfma_f32_16x16x32_bf16 v[16:19], v[176:179], v[218:221], v[16:19]
	v_mfma_f32_16x16x32_bf16 v[4:7], v[168:171], v[226:229], v[4:7]
	v_mfma_f32_16x16x32_bf16 v[0:3], v[176:179], v[226:229], v[0:3]
	v_mfma_f32_16x16x32_bf16 v[52:55], v[172:175], v[206:209], v[52:55]
	v_mfma_f32_16x16x32_bf16 v[48:51], v[194:197], v[206:209], v[48:51]
	v_mfma_f32_16x16x32_bf16 v[36:39], v[172:175], v[214:217], v[36:39]
	v_mfma_f32_16x16x32_bf16 v[32:35], v[194:197], v[214:217], v[32:35]
	v_mfma_f32_16x16x32_bf16 v[20:23], v[172:175], v[222:225], v[20:23]
	v_mfma_f32_16x16x32_bf16 v[16:19], v[194:197], v[222:225], v[16:19]
	v_mfma_f32_16x16x32_bf16 v[4:7], v[172:175], v[230:233], v[4:7]
	v_mfma_f32_16x16x32_bf16 v[0:3], v[194:197], v[230:233], v[0:3]
	s_setprio 0
	s_barrier
	s_add_u32 s42, s42, 0x100
	s_addc_u32 s43, s43, 0
	s_add_u32 s44, s44, 0x100
	s_addc_u32 s45, s45, 0
	s_cmp_ge_u32 s47, s31
	s_mov_b32 s0, s47
	s_cbranch_scc0 .LBB0_482
	s_nop 0
	s_and_b64 vcc, exec, s[66:67]
	s_cbranch_vccz .LBB0_485
	s_barrier
